# per-token finalize item: all four tokens' loads issued at the item head into fresh registers (one wait, carry row loaded once) instead of four serialised load->reduce->store chains
# baseline (speedup 1.0000x reference)
.LBB0_806:
	v_mov_b32_e32 v0, v185
	v_mov_b32_e32 v7, v169
	v_and_b32_e32 v1, 63, v0
	v_ashrrev_i32_e32 v0, 4, v0
	v_and_b32_e32 v0, -4, v0
	v_add_u32_e32 v14, s27, v0
	v_lshlrev_b32_e32 v6, 4, v1
	v_ashrrev_i32_e32 v15, 31, v14
	v_lshl_add_u64 v[12:13], s[6:7], 0, v[6:7]
	v_lshlrev_b64 v[2:3], 10, v[14:15]
	v_lshl_add_u64 v[2:3], v[12:13], 0, v[2:3]
	v_cmp_lt_i32_e32 vcc, v194, v193
	v_lshlrev_b32_e32 v168, 3, v1
	v_lshrrev_b32_e32 v0, 7, v14
	v_ashrrev_i32_e32 v1, 7, v14
	s_movk_i32 s0, 0xffc0
	v_bfi_b32 v0, s0, v1, v0
	v_ashrrev_i32_e32 v1, 31, v0
	v_lshlrev_b64 v[0:1], 10, v[0:1]
	v_lshl_add_u64 v[0:1], s[12:13], 0, v[0:1]
	v_lshl_add_u64 v[4:5], v[0:1], 0, v[6:7]
	v_lshlrev_b64 v[0:1], 11, v[14:15]
	v_lshl_add_u64 v[10:11], s[8:9], 0, v[168:169]
	v_lshl_add_u64 v[8:9], s[10:11], 0, v[168:169]
	v_mov_b32_e32 v160, v14
	v_mov_b32_e32 v161, v15
	v_lshlrev_b64 v[162:163], 10, v[160:161]
	v_lshl_add_u64 v[162:163], v[12:13], 0, v[162:163]
	global_load_dwordx4 v[204:207], v[162:163], off
	v_lshlrev_b64 v[164:165], 9, v[160:161]
	v_lshl_add_u64 v[162:163], v[10:11], 0, v[164:165]
	v_lshl_add_u64 v[164:165], v[8:9], 0, v[164:165]
	global_load_dwordx2 v[220:221], v[162:163], off
	global_load_dwordx2 v[228:229], v[164:165], off
	v_mov_b64_e32 v[166:167], s[82:83]
	s_nop 0
	v_mad_i64_i32 v[166:167], s[0:1], v160, s93, v[166:167]
	v_lshl_add_u64 v[166:167], v[166:167], 0, v[168:169]
	v_add_co_u32_e64 v166, s[0:1], s29, v166
	s_nop 1
	v_addc_co_u32_e64 v167, s[0:1], 0, v167, s[0:1]
	global_load_dwordx2 v[236:237], v[166:167], off offset:3072
	v_add_u32_e32 v160, 1, v14
	v_ashrrev_i32_e32 v161, 31, v160
	v_lshlrev_b64 v[162:163], 10, v[160:161]
	v_lshl_add_u64 v[162:163], v[12:13], 0, v[162:163]
	global_load_dwordx4 v[208:211], v[162:163], off
	v_lshlrev_b64 v[164:165], 9, v[160:161]
	v_lshl_add_u64 v[162:163], v[10:11], 0, v[164:165]
	v_lshl_add_u64 v[164:165], v[8:9], 0, v[164:165]
	global_load_dwordx2 v[222:223], v[162:163], off
	global_load_dwordx2 v[230:231], v[164:165], off
	v_mov_b64_e32 v[166:167], s[82:83]
	s_nop 0
	v_mad_i64_i32 v[166:167], s[0:1], v160, s93, v[166:167]
	v_lshl_add_u64 v[166:167], v[166:167], 0, v[168:169]
	v_add_co_u32_e64 v166, s[0:1], s29, v166
	s_nop 1
	v_addc_co_u32_e64 v167, s[0:1], 0, v167, s[0:1]
	global_load_dwordx2 v[238:239], v[166:167], off offset:3072
	v_add_u32_e32 v160, 2, v14
	v_ashrrev_i32_e32 v161, 31, v160
	v_lshlrev_b64 v[162:163], 10, v[160:161]
	v_lshl_add_u64 v[162:163], v[12:13], 0, v[162:163]
	global_load_dwordx4 v[212:215], v[162:163], off
	v_lshlrev_b64 v[164:165], 9, v[160:161]
	v_lshl_add_u64 v[162:163], v[10:11], 0, v[164:165]
	v_lshl_add_u64 v[164:165], v[8:9], 0, v[164:165]
	global_load_dwordx2 v[224:225], v[162:163], off
	global_load_dwordx2 v[232:233], v[164:165], off
	v_mov_b64_e32 v[166:167], s[82:83]
	s_nop 0
	v_mad_i64_i32 v[166:167], s[0:1], v160, s93, v[166:167]
	v_lshl_add_u64 v[166:167], v[166:167], 0, v[168:169]
	v_add_co_u32_e64 v166, s[0:1], s29, v166
	s_nop 1
	v_addc_co_u32_e64 v167, s[0:1], 0, v167, s[0:1]
	global_load_dwordx2 v[240:241], v[166:167], off offset:3072
	v_add_u32_e32 v160, 3, v14
	v_ashrrev_i32_e32 v161, 31, v160
	v_lshlrev_b64 v[162:163], 10, v[160:161]
	v_lshl_add_u64 v[162:163], v[12:13], 0, v[162:163]
	global_load_dwordx4 v[216:219], v[162:163], off
	v_lshlrev_b64 v[164:165], 9, v[160:161]
	v_lshl_add_u64 v[162:163], v[10:11], 0, v[164:165]
	v_lshl_add_u64 v[164:165], v[8:9], 0, v[164:165]
	global_load_dwordx2 v[226:227], v[162:163], off
	global_load_dwordx2 v[234:235], v[164:165], off
	v_mov_b64_e32 v[166:167], s[82:83]
	s_nop 0
	v_mad_i64_i32 v[166:167], s[0:1], v160, s93, v[166:167]
	v_lshl_add_u64 v[166:167], v[166:167], 0, v[168:169]
	v_add_co_u32_e64 v166, s[0:1], s29, v166
	s_nop 1
	v_addc_co_u32_e64 v167, s[0:1], 0, v167, s[0:1]
	global_load_dwordx2 v[242:243], v[166:167], off offset:3072
	global_load_dwordx4 v[248:251], v[4:5], off
	s_waitcnt vmcnt(0)
	v_mov_b32_e32 v16, v204
	v_mov_b32_e32 v17, v205
	v_mov_b32_e32 v18, v206
	v_mov_b32_e32 v19, v207
	v_and_b32_e32 v21, 0xffff0000, v16
	v_lshlrev_b32_e32 v20, 16, v16
	v_mul_f32_e32 v24, v21, v21
	v_lshlrev_b32_e32 v22, 16, v17
	v_fmac_f32_e32 v24, v20, v20
	v_and_b32_e32 v23, 0xffff0000, v17
	v_fmac_f32_e32 v24, v22, v22
	v_and_b32_e32 v2, 0xffff0000, v18
	v_lshlrev_b32_e32 v3, 16, v18
	v_fmac_f32_e32 v24, v23, v23
	v_pk_mul_f32 v[16:17], v[2:3], v[2:3]
	s_nop 0
	v_add_f32_e32 v17, v17, v24
	v_add_f32_e32 v24, v16, v17
	v_and_b32_e32 v16, 0xffff0000, v19
	v_lshlrev_b32_e32 v17, 16, v19
	v_pk_mul_f32 v[18:19], v[16:17], v[16:17]
	s_nop 0
	v_add_f32_e32 v19, v19, v24
	v_add_f32_e32 v18, v18, v19
	v_cndmask_b32_e32 v19, v191, v194, vcc
	v_lshlrev_b32_e32 v28, 2, v19
	s_nop 1
	v_mov_b32_dpp v19, v18 quad_perm:[1,0,3,2] row_mask:0xf bank_mask:0xf
	v_cmp_lt_i32_e32 vcc, v195, v193
	s_waitcnt lgkmcnt(0)
	v_add_f32_e32 v18, v18, v19
	v_cndmask_b32_e32 v19, v191, v195, vcc
	v_lshlrev_b32_e32 v29, 2, v19
	s_nop 1
	v_mov_b32_dpp v19, v18 quad_perm:[2,3,0,1] row_mask:0xf bank_mask:0xf
	v_cmp_lt_i32_e32 vcc, v196, v193
	s_waitcnt lgkmcnt(0)
	v_add_f32_e32 v18, v18, v19
	v_cndmask_b32_e32 v19, v191, v196, vcc
	v_lshlrev_b32_e32 v30, 2, v19
	s_nop 1
	v_mov_b32_dpp v19, v18 row_half_mirror row_mask:0xf bank_mask:0xf
	v_cmp_lt_i32_e32 vcc, v197, v193
	s_waitcnt lgkmcnt(0)
	v_add_f32_e32 v18, v18, v19
	v_cndmask_b32_e32 v19, v191, v197, vcc
	v_lshlrev_b32_e32 v31, 2, v19
	s_nop 1
	v_mov_b32_dpp v19, v18 row_mirror row_mask:0xf bank_mask:0xf
	v_cmp_lt_i32_e32 vcc, v198, v193
	s_waitcnt lgkmcnt(0)
	v_add_f32_e32 v18, v18, v19
	v_cndmask_b32_e32 v19, v191, v198, vcc
	v_lshlrev_b32_e32 v32, 2, v19
	ds_bpermute_b32 v19, v32, v18
	v_cmp_lt_i32_e32 vcc, v199, v193
	s_waitcnt lgkmcnt(0)
	v_add_f32_e32 v18, v18, v19
	v_cndmask_b32_e32 v19, v191, v199, vcc
	v_lshlrev_b32_e32 v33, 2, v19
	ds_bpermute_b32 v19, v33, v18
	s_waitcnt lgkmcnt(0)
	v_add_f32_e32 v24, v18, v19
	v_lshl_add_u64 v[18:19], s[4:5], 0, v[0:1]
	v_fmamk_f32 v0, v24, 0x3b000000, v187
	v_cmp_gt_f32_e32 vcc, s28, v0
	v_mul_f32_e32 v1, 0x4b800000, v0
	s_nop 0
	v_cndmask_b32_e32 v0, v0, v1, vcc
	v_rsq_f32_e32 v0, v0
	s_nop 0
	v_mul_f32_e32 v1, 0x45800000, v0
	v_cndmask_b32_e32 v24, v0, v1, vcc
	v_mul_f32_e32 v0, v24, v20
	v_mul_f32_e32 v1, v24, v21
	v_mul_f32_e32 v3, v24, v3
	v_mul_f32_e32 v2, v24, v2
	v_cvt_pk_bf16_f32 v0, v0, v1
	v_mul_f32_e32 v1, v24, v22
	v_mul_f32_e32 v20, v24, v23
	v_cvt_pk_bf16_f32 v2, v3, v2
	v_mul_f32_e32 v3, v24, v17
	v_mul_f32_e32 v16, v24, v16
	v_cvt_pk_bf16_f32 v1, v1, v20
	v_cvt_pk_bf16_f32 v3, v3, v16
	v_lshl_add_u64 v[16:17], v[18:19], 0, v[6:7]
	global_store_dwordx4 v[16:17], v[0:3], off
	v_mov_b64_e32 v[16:17], s[82:83]
	s_nop 0
	v_lshlrev_b64 v[0:1], 9, v[14:15]
	v_lshl_add_u64 v[2:3], v[10:11], 0, v[0:1]
	v_lshl_add_u64 v[0:1], v[8:9], 0, v[0:1]
	v_mov_b32_e32 v24, v220
	v_mov_b32_e32 v25, v221
	v_mov_b32_e32 v22, v228
	v_mov_b32_e32 v23, v229
	v_mad_i64_i32 v[0:1], s[0:1], v14, s93, v[16:17]
	v_lshl_add_u64 v[0:1], v[0:1], 0, v[168:169]
	v_add_co_u32_e32 v0, vcc, s29, v0
	v_lshlrev_b32_e32 v20, 16, v25
	v_addc_co_u32_e32 v1, vcc, 0, v1, vcc
	v_mov_b32_e32 v26, v236
	v_mov_b32_e32 v27, v237
	s_nop 0
	v_mov_b32_e32 v0, v248
	v_mov_b32_e32 v1, v249
	v_mov_b32_e32 v2, v250
	v_mov_b32_e32 v3, v251
	v_lshlrev_b32_e32 v34, 16, v23
	v_and_b32_e32 v35, 0xffff0000, v23
	v_and_b32_e32 v21, 0xffff0000, v25
	v_lshlrev_b32_e32 v36, 16, v27
	v_mul_f32_e32 v15, 0x3d372713, v36
	v_mul_f32_e32 v15, v15, v36
	v_mov_b32_e32 v23, v36
	v_fmac_f32_e32 v23, v15, v23
	v_mul_f32_e32 v15, 0x3f4c422a, v23
	v_add_f32_e32 v15, v15, v15
	v_and_b32_e32 v37, 0xffff0000, v27
	v_mul_f32_e32 v15, 0x3fb8aa3b, v15
	v_exp_f32_e32 v38, v15
	v_mul_f32_e32 v15, 0x3d372713, v37
	v_pk_fma_f32 v[2:3], v[2:3], v[34:35], v[20:21]
	v_mul_f32_e32 v15, v15, v37
	v_mov_b32_e32 v20, v37
	v_fmac_f32_e32 v20, v15, v20
	v_mul_f32_e32 v15, 0x3f4c422a, v20
	v_add_f32_e32 v15, v15, v15
	v_mul_f32_e32 v15, 0x3fb8aa3b, v15
	v_exp_f32_e32 v39, v15
	s_nop 0
	v_pk_add_f32 v[20:21], v[38:39], 1.0 op_sel_hi:[1,0]
	s_nop 0
	v_div_scale_f32 v15, s[0:1], v21, v21, 2.0
	v_rcp_f32_e32 v23, v15
	s_nop 0
	v_fma_f32 v25, -v15, v23, 1.0
	v_fmac_f32_e32 v23, v25, v23
	v_div_scale_f32 v25, vcc, 2.0, v21, 2.0
	v_mul_f32_e32 v27, v25, v23
	v_fma_f32 v34, -v15, v27, v25
	v_fmac_f32_e32 v27, v34, v23
	v_fma_f32 v15, -v15, v27, v25
	v_div_fmas_f32 v15, v15, v23, v27
	v_div_fixup_f32 v21, v15, v21, 2.0
	v_div_scale_f32 v15, s[0:1], v20, v20, 2.0
	v_rcp_f32_e32 v23, v15
	s_nop 0
	v_fma_f32 v25, -v15, v23, 1.0
	v_fmac_f32_e32 v23, v25, v23
	v_div_scale_f32 v25, vcc, 2.0, v20, 2.0
	v_mul_f32_e32 v27, v25, v23
	v_fma_f32 v34, -v15, v27, v25
	v_fmac_f32_e32 v27, v34, v23
	v_fma_f32 v15, -v15, v27, v25
	v_div_fmas_f32 v15, v15, v23, v27
	v_div_fixup_f32 v20, v15, v20, 2.0
	v_pk_add_f32 v[20:21], v[20:21], 1.0 op_sel_hi:[1,0] neg_lo:[1,0] neg_hi:[1,0]
	v_pk_mul_f32 v[34:35], v[36:37], 0.5 op_sel_hi:[1,0]
	v_pk_add_f32 v[20:21], v[20:21], 1.0 op_sel_hi:[1,0]
	v_lshlrev_b32_e32 v36, 16, v22
	v_pk_mul_f32 v[20:21], v[34:35], v[20:21]
	v_lshlrev_b32_e32 v34, 16, v24
	v_and_b32_e32 v35, 0xffff0000, v24
	v_lshlrev_b32_e32 v24, 16, v26
	v_mul_f32_e32 v15, 0x3d372713, v24
	v_and_b32_e32 v37, 0xffff0000, v22
	v_mul_f32_e32 v15, v15, v24
	v_mov_b32_e32 v22, v24
	v_fmac_f32_e32 v22, v15, v22
	v_mul_f32_e32 v15, 0x3f4c422a, v22
	v_add_f32_e32 v15, v15, v15
	v_and_b32_e32 v25, 0xffff0000, v26
	v_mul_f32_e32 v15, 0x3fb8aa3b, v15
	v_exp_f32_e32 v22, v15
	v_mul_f32_e32 v15, 0x3d372713, v25
	v_mul_f32_e32 v15, v15, v25
	v_mov_b32_e32 v23, v25
	v_fmac_f32_e32 v23, v15, v23
	v_mul_f32_e32 v15, 0x3f4c422a, v23
	v_add_f32_e32 v15, v15, v15
	v_mul_f32_e32 v15, 0x3fb8aa3b, v15
	v_exp_f32_e32 v23, v15
	v_pk_fma_f32 v[0:1], v[0:1], v[36:37], v[34:35]
	v_pk_mul_f32 v[24:25], v[24:25], 0.5 op_sel_hi:[1,0]
	v_pk_mul_f32 v[2:3], v[2:3], v[20:21]
	v_pk_add_f32 v[22:23], v[22:23], 1.0 op_sel_hi:[1,0]
	v_pk_mul_f32 v[20:21], v[2:3], v[2:3]
	v_div_scale_f32 v15, s[0:1], v23, v23, 2.0
	v_rcp_f32_e32 v26, v15
	s_nop 0
	v_fma_f32 v27, -v15, v26, 1.0
	v_fmac_f32_e32 v26, v27, v26
	v_div_scale_f32 v27, vcc, 2.0, v23, 2.0
	v_mul_f32_e32 v34, v27, v26
	v_fma_f32 v35, -v15, v34, v27
	v_fmac_f32_e32 v34, v35, v26
	v_fma_f32 v15, -v15, v34, v27
	v_div_fmas_f32 v15, v15, v26, v34
	v_div_fixup_f32 v23, v15, v23, 2.0
	v_div_scale_f32 v15, s[0:1], v22, v22, 2.0
	v_rcp_f32_e32 v26, v15
	s_nop 0
	v_fma_f32 v27, -v15, v26, 1.0
	v_fmac_f32_e32 v26, v27, v26
	v_div_scale_f32 v27, vcc, 2.0, v22, 2.0
	v_mul_f32_e32 v34, v27, v26
	v_fma_f32 v35, -v15, v34, v27
	v_fmac_f32_e32 v34, v35, v26
	v_fma_f32 v15, -v15, v34, v27
	v_div_fmas_f32 v15, v15, v26, v34
	v_div_fixup_f32 v22, v15, v22, 2.0
	v_pk_add_f32 v[22:23], v[22:23], 1.0 op_sel_hi:[1,0] neg_lo:[1,0] neg_hi:[1,0]
	s_nop 0
	v_pk_add_f32 v[22:23], v[22:23], 1.0 op_sel_hi:[1,0]
	s_nop 0
	v_pk_mul_f32 v[22:23], v[24:25], v[22:23]
	s_nop 0
	v_pk_mul_f32 v[0:1], v[0:1], v[22:23]
	s_nop 0
	v_pk_mul_f32 v[22:23], v[0:1], v[0:1]
	s_nop 0
	v_add_f32_e32 v15, v22, v23
	v_add_f32_e32 v15, v20, v15
	v_add_f32_e32 v15, v21, v15
	s_nop 1
	v_mov_b32_dpp v20, v15 quad_perm:[1,0,3,2] row_mask:0xf bank_mask:0xf
	s_waitcnt lgkmcnt(0)
	v_add_f32_e32 v15, v15, v20
	s_nop 1
	v_mov_b32_dpp v20, v15 quad_perm:[2,3,0,1] row_mask:0xf bank_mask:0xf
	s_waitcnt lgkmcnt(0)
	v_add_f32_e32 v15, v15, v20
	s_nop 1
	v_mov_b32_dpp v20, v15 row_half_mirror row_mask:0xf bank_mask:0xf
	s_waitcnt lgkmcnt(0)
	v_add_f32_e32 v15, v15, v20
	s_nop 1
	v_mov_b32_dpp v20, v15 row_mirror row_mask:0xf bank_mask:0xf
	s_waitcnt lgkmcnt(0)
	v_add_f32_e32 v15, v15, v20
	ds_bpermute_b32 v20, v32, v15
	s_waitcnt lgkmcnt(0)
	v_add_f32_e32 v15, v15, v20
	ds_bpermute_b32 v20, v33, v15
	s_waitcnt lgkmcnt(0)
	v_add_f32_e32 v15, v15, v20
	v_fmamk_f32 v15, v15, 0x3b800000, v187
	v_cmp_gt_f32_e32 vcc, s28, v15
	v_mul_f32_e32 v20, 0x4b800000, v15
	s_nop 0
	v_cndmask_b32_e32 v15, v15, v20, vcc
	v_rsq_f32_e32 v15, v15
	s_nop 0
	v_mul_f32_e32 v20, 0x45800000, v15
	v_cndmask_b32_e32 v20, v15, v20, vcc
	v_pk_mul_f32 v[0:1], v[0:1], v[20:21] op_sel_hi:[1,0]
	v_pk_mul_f32 v[2:3], v[2:3], v[20:21] op_sel_hi:[1,0]
	v_cvt_pk_bf16_f32 v0, v0, v1
	v_cvt_pk_bf16_f32 v1, v2, v3
	v_lshl_add_u64 v[2:3], v[18:19], 0, v[168:169]
	global_store_dwordx2 v[2:3], v[0:1], off offset:1536
	v_add_u32_e32 v0, 1, v14
	v_ashrrev_i32_e32 v1, 31, v0
	v_lshlrev_b64 v[18:19], 10, v[0:1]
	v_lshl_add_u64 v[18:19], v[12:13], 0, v[18:19]
	v_mov_b32_e32 v18, v208
	v_mov_b32_e32 v19, v209
	v_mov_b32_e32 v20, v210
	v_mov_b32_e32 v21, v211
	v_lshlrev_b64 v[2:3], 11, v[0:1]
	v_and_b32_e32 v26, 0xffff0000, v18
	v_lshlrev_b32_e32 v15, 16, v18
	v_mul_f32_e32 v24, v26, v26
	v_lshlrev_b32_e32 v27, 16, v19
	v_fmac_f32_e32 v24, v15, v15
	v_and_b32_e32 v34, 0xffff0000, v19
	v_fmac_f32_e32 v24, v27, v27
	v_and_b32_e32 v22, 0xffff0000, v20
	v_lshlrev_b32_e32 v23, 16, v20
	v_fmac_f32_e32 v24, v34, v34
	v_pk_mul_f32 v[18:19], v[22:23], v[22:23]
	v_lshlrev_b32_e32 v25, 16, v21
	v_add_f32_e32 v19, v19, v24
	v_and_b32_e32 v24, 0xffff0000, v21
	v_add_f32_e32 v20, v18, v19
	v_pk_mul_f32 v[18:19], v[24:25], v[24:25]
	s_nop 0
	v_add_f32_e32 v19, v19, v20
	v_add_f32_e32 v18, v18, v19
	s_nop 1
	v_mov_b32_dpp v19, v18 quad_perm:[1,0,3,2] row_mask:0xf bank_mask:0xf
	s_waitcnt lgkmcnt(0)
	v_add_f32_e32 v18, v18, v19
	s_nop 1
	v_mov_b32_dpp v19, v18 quad_perm:[2,3,0,1] row_mask:0xf bank_mask:0xf
	s_waitcnt lgkmcnt(0)
	v_add_f32_e32 v18, v18, v19
	s_nop 1
	v_mov_b32_dpp v19, v18 row_half_mirror row_mask:0xf bank_mask:0xf
	s_waitcnt lgkmcnt(0)
	v_add_f32_e32 v18, v18, v19
	s_nop 1
	v_mov_b32_dpp v19, v18 row_mirror row_mask:0xf bank_mask:0xf
	s_waitcnt lgkmcnt(0)
	v_add_f32_e32 v18, v18, v19
	ds_bpermute_b32 v19, v32, v18
	s_waitcnt lgkmcnt(0)
	v_add_f32_e32 v18, v18, v19
	ds_bpermute_b32 v19, v33, v18
	s_waitcnt lgkmcnt(0)
	v_add_f32_e32 v20, v18, v19
	v_lshl_add_u64 v[18:19], s[4:5], 0, v[2:3]
	v_fmamk_f32 v2, v20, 0x3b000000, v187
	v_cmp_gt_f32_e32 vcc, s28, v2
	v_mul_f32_e32 v3, 0x4b800000, v2
	s_nop 0
	v_cndmask_b32_e32 v2, v2, v3, vcc
	v_rsq_f32_e32 v2, v2
	s_nop 0
	v_mul_f32_e32 v3, 0x45800000, v2
	v_cndmask_b32_e32 v2, v2, v3, vcc
	v_mul_f32_e32 v3, v2, v15
	v_mul_f32_e32 v15, v2, v26
	v_cvt_pk_bf16_f32 v20, v3, v15
	v_mul_f32_e32 v3, v2, v27
	v_mul_f32_e32 v15, v2, v34
	v_cvt_pk_bf16_f32 v21, v3, v15
	v_mul_f32_e32 v3, v2, v23
	v_mul_f32_e32 v15, v2, v22
	v_cvt_pk_bf16_f32 v22, v3, v15
	v_mul_f32_e32 v3, v2, v25
	v_mul_f32_e32 v2, v2, v24
	v_cvt_pk_bf16_f32 v23, v3, v2
	v_lshl_add_u64 v[2:3], v[18:19], 0, v[6:7]
	global_store_dwordx4 v[2:3], v[20:23], off
	v_lshlrev_b64 v[2:3], 9, v[0:1]
	v_mad_i64_i32 v[0:1], s[0:1], v0, s93, v[16:17]
	v_lshl_add_u64 v[0:1], v[0:1], 0, v[168:169]
	v_add_co_u32_e32 v0, vcc, s29, v0
	v_lshl_add_u64 v[20:21], v[10:11], 0, v[2:3]
	v_lshl_add_u64 v[2:3], v[8:9], 0, v[2:3]
	v_addc_co_u32_e32 v1, vcc, 0, v1, vcc
	v_mov_b32_e32 v24, v222
	v_mov_b32_e32 v25, v223
	v_mov_b32_e32 v22, v230
	v_mov_b32_e32 v23, v231
	v_mov_b32_e32 v26, v238
	v_mov_b32_e32 v27, v239
	s_nop 0
	v_mov_b32_e32 v0, v248
	v_mov_b32_e32 v1, v249
	v_mov_b32_e32 v2, v250
	v_mov_b32_e32 v3, v251
	v_lshlrev_b32_e32 v20, 16, v25
	v_lshlrev_b32_e32 v36, 16, v27
	v_mul_f32_e32 v15, 0x3d372713, v36
	v_lshlrev_b32_e32 v34, 16, v23
	v_and_b32_e32 v35, 0xffff0000, v23
	v_mul_f32_e32 v15, v15, v36
	v_mov_b32_e32 v23, v36
	v_fmac_f32_e32 v23, v15, v23
	v_mul_f32_e32 v15, 0x3f4c422a, v23
	v_add_f32_e32 v15, v15, v15
	v_and_b32_e32 v37, 0xffff0000, v27
	v_mul_f32_e32 v15, 0x3fb8aa3b, v15
	v_and_b32_e32 v21, 0xffff0000, v25
	v_exp_f32_e32 v38, v15
	v_mul_f32_e32 v15, 0x3d372713, v37
	v_pk_fma_f32 v[2:3], v[2:3], v[34:35], v[20:21]
	v_mul_f32_e32 v15, v15, v37
	v_mov_b32_e32 v20, v37
	v_fmac_f32_e32 v20, v15, v20
	v_mul_f32_e32 v15, 0x3f4c422a, v20
	v_add_f32_e32 v15, v15, v15
	v_mul_f32_e32 v15, 0x3fb8aa3b, v15
	v_exp_f32_e32 v39, v15
	s_nop 0
	v_pk_add_f32 v[20:21], v[38:39], 1.0 op_sel_hi:[1,0]
	s_nop 0
	v_div_scale_f32 v15, s[0:1], v21, v21, 2.0
	v_rcp_f32_e32 v23, v15
	s_nop 0
	v_fma_f32 v25, -v15, v23, 1.0
	v_fmac_f32_e32 v23, v25, v23
	v_div_scale_f32 v25, vcc, 2.0, v21, 2.0
	v_mul_f32_e32 v27, v25, v23
	v_fma_f32 v34, -v15, v27, v25
	v_fmac_f32_e32 v27, v34, v23
	v_fma_f32 v15, -v15, v27, v25
	v_div_fmas_f32 v15, v15, v23, v27
	v_div_fixup_f32 v21, v15, v21, 2.0
	v_div_scale_f32 v15, s[0:1], v20, v20, 2.0
	v_rcp_f32_e32 v23, v15
	s_nop 0
	v_fma_f32 v25, -v15, v23, 1.0
	v_fmac_f32_e32 v23, v25, v23
	v_div_scale_f32 v25, vcc, 2.0, v20, 2.0
	v_mul_f32_e32 v27, v25, v23
	v_fma_f32 v34, -v15, v27, v25
	v_fmac_f32_e32 v27, v34, v23
	v_fma_f32 v15, -v15, v27, v25
	v_div_fmas_f32 v15, v15, v23, v27
	v_div_fixup_f32 v20, v15, v20, 2.0
	v_pk_add_f32 v[20:21], v[20:21], 1.0 op_sel_hi:[1,0] neg_lo:[1,0] neg_hi:[1,0]
	v_pk_mul_f32 v[34:35], v[36:37], 0.5 op_sel_hi:[1,0]
	v_pk_add_f32 v[20:21], v[20:21], 1.0 op_sel_hi:[1,0]
	v_lshlrev_b32_e32 v36, 16, v22
	v_pk_mul_f32 v[20:21], v[34:35], v[20:21]
	v_lshlrev_b32_e32 v34, 16, v24
	v_and_b32_e32 v35, 0xffff0000, v24
	v_lshlrev_b32_e32 v24, 16, v26
	v_mul_f32_e32 v15, 0x3d372713, v24
	v_and_b32_e32 v37, 0xffff0000, v22
	v_mul_f32_e32 v15, v15, v24
	v_mov_b32_e32 v22, v24
	v_fmac_f32_e32 v22, v15, v22
	v_mul_f32_e32 v15, 0x3f4c422a, v22
	v_add_f32_e32 v15, v15, v15
	v_and_b32_e32 v25, 0xffff0000, v26
	v_mul_f32_e32 v15, 0x3fb8aa3b, v15
	v_exp_f32_e32 v22, v15
	v_mul_f32_e32 v15, 0x3d372713, v25
	v_mul_f32_e32 v15, v15, v25
	v_mov_b32_e32 v23, v25
	v_fmac_f32_e32 v23, v15, v23
	v_mul_f32_e32 v15, 0x3f4c422a, v23
	v_add_f32_e32 v15, v15, v15
	v_mul_f32_e32 v15, 0x3fb8aa3b, v15
	v_exp_f32_e32 v23, v15
	v_pk_fma_f32 v[0:1], v[0:1], v[36:37], v[34:35]
	v_pk_mul_f32 v[24:25], v[24:25], 0.5 op_sel_hi:[1,0]
	v_pk_mul_f32 v[2:3], v[2:3], v[20:21]
	v_pk_add_f32 v[22:23], v[22:23], 1.0 op_sel_hi:[1,0]
	v_pk_mul_f32 v[20:21], v[2:3], v[2:3]
	v_div_scale_f32 v15, s[0:1], v23, v23, 2.0
	v_rcp_f32_e32 v26, v15
	s_nop 0
	v_fma_f32 v27, -v15, v26, 1.0
	v_fmac_f32_e32 v26, v27, v26
	v_div_scale_f32 v27, vcc, 2.0, v23, 2.0
	v_mul_f32_e32 v34, v27, v26
	v_fma_f32 v35, -v15, v34, v27
	v_fmac_f32_e32 v34, v35, v26
	v_fma_f32 v15, -v15, v34, v27
	v_div_fmas_f32 v15, v15, v26, v34
	v_div_fixup_f32 v23, v15, v23, 2.0
	v_div_scale_f32 v15, s[0:1], v22, v22, 2.0
	v_rcp_f32_e32 v26, v15
	s_nop 0
	v_fma_f32 v27, -v15, v26, 1.0
	v_fmac_f32_e32 v26, v27, v26
	v_div_scale_f32 v27, vcc, 2.0, v22, 2.0
	v_mul_f32_e32 v34, v27, v26
	v_fma_f32 v35, -v15, v34, v27
	v_fmac_f32_e32 v34, v35, v26
	v_fma_f32 v15, -v15, v34, v27
	v_div_fmas_f32 v15, v15, v26, v34
	v_div_fixup_f32 v22, v15, v22, 2.0
	v_pk_add_f32 v[22:23], v[22:23], 1.0 op_sel_hi:[1,0] neg_lo:[1,0] neg_hi:[1,0]
	s_nop 0
	v_pk_add_f32 v[22:23], v[22:23], 1.0 op_sel_hi:[1,0]
	s_nop 0
	v_pk_mul_f32 v[22:23], v[24:25], v[22:23]
	s_nop 0
	v_pk_mul_f32 v[0:1], v[0:1], v[22:23]
	s_nop 0
	v_pk_mul_f32 v[22:23], v[0:1], v[0:1]
	s_nop 0
	v_add_f32_e32 v15, v22, v23
	v_add_f32_e32 v15, v20, v15
	v_add_f32_e32 v15, v21, v15
	s_nop 1
	v_mov_b32_dpp v20, v15 quad_perm:[1,0,3,2] row_mask:0xf bank_mask:0xf
	s_waitcnt lgkmcnt(0)
	v_add_f32_e32 v15, v15, v20
	s_nop 1
	v_mov_b32_dpp v20, v15 quad_perm:[2,3,0,1] row_mask:0xf bank_mask:0xf
	s_waitcnt lgkmcnt(0)
	v_add_f32_e32 v15, v15, v20
	s_nop 1
	v_mov_b32_dpp v20, v15 row_half_mirror row_mask:0xf bank_mask:0xf
	s_waitcnt lgkmcnt(0)
	v_add_f32_e32 v15, v15, v20
	s_nop 1
	v_mov_b32_dpp v20, v15 row_mirror row_mask:0xf bank_mask:0xf
	s_waitcnt lgkmcnt(0)
	v_add_f32_e32 v15, v15, v20
	ds_bpermute_b32 v20, v32, v15
	s_waitcnt lgkmcnt(0)
	v_add_f32_e32 v15, v15, v20
	ds_bpermute_b32 v20, v33, v15
	s_waitcnt lgkmcnt(0)
	v_add_f32_e32 v15, v15, v20
	v_fmamk_f32 v15, v15, 0x3b800000, v187
	v_cmp_gt_f32_e32 vcc, s28, v15
	v_mul_f32_e32 v20, 0x4b800000, v15
	s_nop 0
	v_cndmask_b32_e32 v15, v15, v20, vcc
	v_rsq_f32_e32 v15, v15
	s_nop 0
	v_mul_f32_e32 v20, 0x45800000, v15
	v_cndmask_b32_e32 v20, v15, v20, vcc
	v_pk_mul_f32 v[0:1], v[0:1], v[20:21] op_sel_hi:[1,0]
	v_pk_mul_f32 v[2:3], v[2:3], v[20:21] op_sel_hi:[1,0]
	v_cvt_pk_bf16_f32 v0, v0, v1
	v_cvt_pk_bf16_f32 v1, v2, v3
	v_lshl_add_u64 v[2:3], v[18:19], 0, v[168:169]
	global_store_dwordx2 v[2:3], v[0:1], off offset:1536
	v_add_u32_e32 v0, 2, v14
	v_ashrrev_i32_e32 v1, 31, v0
	v_lshlrev_b64 v[18:19], 10, v[0:1]
	v_lshl_add_u64 v[18:19], v[12:13], 0, v[18:19]
	v_mov_b32_e32 v18, v212
	v_mov_b32_e32 v19, v213
	v_mov_b32_e32 v20, v214
	v_mov_b32_e32 v21, v215
	v_lshlrev_b64 v[2:3], 11, v[0:1]
	v_and_b32_e32 v26, 0xffff0000, v18
	v_lshlrev_b32_e32 v15, 16, v18
	v_mul_f32_e32 v24, v26, v26
	v_lshlrev_b32_e32 v27, 16, v19
	v_fmac_f32_e32 v24, v15, v15
	v_and_b32_e32 v34, 0xffff0000, v19
	v_fmac_f32_e32 v24, v27, v27
	v_and_b32_e32 v22, 0xffff0000, v20
	v_lshlrev_b32_e32 v23, 16, v20
	v_fmac_f32_e32 v24, v34, v34
	v_pk_mul_f32 v[18:19], v[22:23], v[22:23]
	v_lshlrev_b32_e32 v25, 16, v21
	v_add_f32_e32 v19, v19, v24
	v_and_b32_e32 v24, 0xffff0000, v21
	v_add_f32_e32 v20, v18, v19
	v_pk_mul_f32 v[18:19], v[24:25], v[24:25]
	s_nop 0
	v_add_f32_e32 v19, v19, v20
	v_add_f32_e32 v18, v18, v19
	s_nop 1
	v_mov_b32_dpp v19, v18 quad_perm:[1,0,3,2] row_mask:0xf bank_mask:0xf
	s_waitcnt lgkmcnt(0)
	v_add_f32_e32 v18, v18, v19
	s_nop 1
	v_mov_b32_dpp v19, v18 quad_perm:[2,3,0,1] row_mask:0xf bank_mask:0xf
	s_waitcnt lgkmcnt(0)
	v_add_f32_e32 v18, v18, v19
	s_nop 1
	v_mov_b32_dpp v19, v18 row_half_mirror row_mask:0xf bank_mask:0xf
	s_waitcnt lgkmcnt(0)
	v_add_f32_e32 v18, v18, v19
	s_nop 1
	v_mov_b32_dpp v19, v18 row_mirror row_mask:0xf bank_mask:0xf
	s_waitcnt lgkmcnt(0)
	v_add_f32_e32 v18, v18, v19
	ds_bpermute_b32 v19, v32, v18
	s_waitcnt lgkmcnt(0)
	v_add_f32_e32 v18, v18, v19
	ds_bpermute_b32 v19, v33, v18
	s_waitcnt lgkmcnt(0)
	v_add_f32_e32 v20, v18, v19
	v_lshl_add_u64 v[18:19], s[4:5], 0, v[2:3]
	v_fmamk_f32 v2, v20, 0x3b000000, v187
	v_cmp_gt_f32_e32 vcc, s28, v2
	v_mul_f32_e32 v3, 0x4b800000, v2
	s_nop 0
	v_cndmask_b32_e32 v2, v2, v3, vcc
	v_rsq_f32_e32 v2, v2
	s_nop 0
	v_mul_f32_e32 v3, 0x45800000, v2
	v_cndmask_b32_e32 v2, v2, v3, vcc
	v_mul_f32_e32 v3, v2, v15
	v_mul_f32_e32 v15, v2, v26
	v_cvt_pk_bf16_f32 v20, v3, v15
	v_mul_f32_e32 v3, v2, v27
	v_mul_f32_e32 v15, v2, v34
	v_cvt_pk_bf16_f32 v21, v3, v15
	v_mul_f32_e32 v3, v2, v23
	v_mul_f32_e32 v15, v2, v22
	v_cvt_pk_bf16_f32 v22, v3, v15
	v_mul_f32_e32 v3, v2, v25
	v_mul_f32_e32 v2, v2, v24
	v_cvt_pk_bf16_f32 v23, v3, v2
	v_lshl_add_u64 v[2:3], v[18:19], 0, v[6:7]
	global_store_dwordx4 v[2:3], v[20:23], off
	v_lshlrev_b64 v[2:3], 9, v[0:1]
	v_mad_i64_i32 v[0:1], s[0:1], v0, s93, v[16:17]
	v_lshl_add_u64 v[0:1], v[0:1], 0, v[168:169]
	v_add_co_u32_e32 v0, vcc, s29, v0
	v_lshl_add_u64 v[20:21], v[10:11], 0, v[2:3]
	v_lshl_add_u64 v[2:3], v[8:9], 0, v[2:3]
	v_addc_co_u32_e32 v1, vcc, 0, v1, vcc
	v_mov_b32_e32 v24, v224
	v_mov_b32_e32 v25, v225
	v_mov_b32_e32 v22, v232
	v_mov_b32_e32 v23, v233
	v_mov_b32_e32 v26, v240
	v_mov_b32_e32 v27, v241
	s_nop 0
	v_mov_b32_e32 v0, v248
	v_mov_b32_e32 v1, v249
	v_mov_b32_e32 v2, v250
	v_mov_b32_e32 v3, v251
	v_lshlrev_b32_e32 v20, 16, v25
	v_lshlrev_b32_e32 v36, 16, v27
	v_mul_f32_e32 v15, 0x3d372713, v36
	v_lshlrev_b32_e32 v34, 16, v23
	v_and_b32_e32 v35, 0xffff0000, v23
	v_mul_f32_e32 v15, v15, v36
	v_mov_b32_e32 v23, v36
	v_fmac_f32_e32 v23, v15, v23
	v_mul_f32_e32 v15, 0x3f4c422a, v23
	v_add_f32_e32 v15, v15, v15
	v_and_b32_e32 v37, 0xffff0000, v27
	v_mul_f32_e32 v15, 0x3fb8aa3b, v15
	v_and_b32_e32 v21, 0xffff0000, v25
	v_exp_f32_e32 v38, v15
	v_mul_f32_e32 v15, 0x3d372713, v37
	v_pk_fma_f32 v[2:3], v[2:3], v[34:35], v[20:21]
	v_mul_f32_e32 v15, v15, v37
	v_mov_b32_e32 v20, v37
	v_fmac_f32_e32 v20, v15, v20
	v_mul_f32_e32 v15, 0x3f4c422a, v20
	v_add_f32_e32 v15, v15, v15
	v_mul_f32_e32 v15, 0x3fb8aa3b, v15
	v_exp_f32_e32 v39, v15
	s_nop 0
	v_pk_add_f32 v[20:21], v[38:39], 1.0 op_sel_hi:[1,0]
	s_nop 0
	v_div_scale_f32 v15, s[0:1], v21, v21, 2.0
	v_rcp_f32_e32 v23, v15
	s_nop 0
	v_fma_f32 v25, -v15, v23, 1.0
	v_fmac_f32_e32 v23, v25, v23
	v_div_scale_f32 v25, vcc, 2.0, v21, 2.0
	v_mul_f32_e32 v27, v25, v23
	v_fma_f32 v34, -v15, v27, v25
	v_fmac_f32_e32 v27, v34, v23
	v_fma_f32 v15, -v15, v27, v25
	v_div_fmas_f32 v15, v15, v23, v27
	v_div_fixup_f32 v21, v15, v21, 2.0
	v_div_scale_f32 v15, s[0:1], v20, v20, 2.0
	v_rcp_f32_e32 v23, v15
	s_nop 0
	v_fma_f32 v25, -v15, v23, 1.0
	v_fmac_f32_e32 v23, v25, v23
	v_div_scale_f32 v25, vcc, 2.0, v20, 2.0
	v_mul_f32_e32 v27, v25, v23
	v_fma_f32 v34, -v15, v27, v25
	v_fmac_f32_e32 v27, v34, v23
	v_fma_f32 v15, -v15, v27, v25
	v_div_fmas_f32 v15, v15, v23, v27
	v_div_fixup_f32 v20, v15, v20, 2.0
	v_pk_add_f32 v[20:21], v[20:21], 1.0 op_sel_hi:[1,0] neg_lo:[1,0] neg_hi:[1,0]
	v_pk_mul_f32 v[34:35], v[36:37], 0.5 op_sel_hi:[1,0]
	v_pk_add_f32 v[20:21], v[20:21], 1.0 op_sel_hi:[1,0]
	v_lshlrev_b32_e32 v36, 16, v22
	v_pk_mul_f32 v[20:21], v[34:35], v[20:21]
	v_lshlrev_b32_e32 v34, 16, v24
	v_and_b32_e32 v35, 0xffff0000, v24
	v_lshlrev_b32_e32 v24, 16, v26
	v_mul_f32_e32 v15, 0x3d372713, v24
	v_and_b32_e32 v37, 0xffff0000, v22
	v_mul_f32_e32 v15, v15, v24
	v_mov_b32_e32 v22, v24
	v_fmac_f32_e32 v22, v15, v22
	v_mul_f32_e32 v15, 0x3f4c422a, v22
	v_add_f32_e32 v15, v15, v15
	v_and_b32_e32 v25, 0xffff0000, v26
	v_mul_f32_e32 v15, 0x3fb8aa3b, v15
	v_exp_f32_e32 v22, v15
	v_mul_f32_e32 v15, 0x3d372713, v25
	v_mul_f32_e32 v15, v15, v25
	v_mov_b32_e32 v23, v25
	v_fmac_f32_e32 v23, v15, v23
	v_mul_f32_e32 v15, 0x3f4c422a, v23
	v_add_f32_e32 v15, v15, v15
	v_mul_f32_e32 v15, 0x3fb8aa3b, v15
	v_exp_f32_e32 v23, v15
	v_pk_fma_f32 v[0:1], v[0:1], v[36:37], v[34:35]
	v_pk_mul_f32 v[24:25], v[24:25], 0.5 op_sel_hi:[1,0]
	v_pk_mul_f32 v[2:3], v[2:3], v[20:21]
	v_pk_add_f32 v[22:23], v[22:23], 1.0 op_sel_hi:[1,0]
	v_pk_mul_f32 v[20:21], v[2:3], v[2:3]
	v_div_scale_f32 v15, s[0:1], v23, v23, 2.0
	v_rcp_f32_e32 v26, v15
	s_nop 0
	v_fma_f32 v27, -v15, v26, 1.0
	v_fmac_f32_e32 v26, v27, v26
	v_div_scale_f32 v27, vcc, 2.0, v23, 2.0
	v_mul_f32_e32 v34, v27, v26
	v_fma_f32 v35, -v15, v34, v27
	v_fmac_f32_e32 v34, v35, v26
	v_fma_f32 v15, -v15, v34, v27
	v_div_fmas_f32 v15, v15, v26, v34
	v_div_fixup_f32 v23, v15, v23, 2.0
	v_div_scale_f32 v15, s[0:1], v22, v22, 2.0
	v_rcp_f32_e32 v26, v15
	s_nop 0
	v_fma_f32 v27, -v15, v26, 1.0
	v_fmac_f32_e32 v26, v27, v26
	v_div_scale_f32 v27, vcc, 2.0, v22, 2.0
	v_mul_f32_e32 v34, v27, v26
	v_fma_f32 v35, -v15, v34, v27
	v_fmac_f32_e32 v34, v35, v26
	v_fma_f32 v15, -v15, v34, v27
	v_div_fmas_f32 v15, v15, v26, v34
	v_div_fixup_f32 v22, v15, v22, 2.0
	v_pk_add_f32 v[22:23], v[22:23], 1.0 op_sel_hi:[1,0] neg_lo:[1,0] neg_hi:[1,0]
	s_nop 0
	v_pk_add_f32 v[22:23], v[22:23], 1.0 op_sel_hi:[1,0]
	s_nop 0
	v_pk_mul_f32 v[22:23], v[24:25], v[22:23]
	s_nop 0
	v_pk_mul_f32 v[0:1], v[0:1], v[22:23]
	s_nop 0
	v_pk_mul_f32 v[22:23], v[0:1], v[0:1]
	s_nop 0
	v_add_f32_e32 v15, v22, v23
	v_add_f32_e32 v15, v20, v15
	v_add_f32_e32 v15, v21, v15
	s_nop 1
	v_mov_b32_dpp v20, v15 quad_perm:[1,0,3,2] row_mask:0xf bank_mask:0xf
	s_waitcnt lgkmcnt(0)
	v_add_f32_e32 v15, v15, v20
	s_nop 1
	v_mov_b32_dpp v20, v15 quad_perm:[2,3,0,1] row_mask:0xf bank_mask:0xf
	s_waitcnt lgkmcnt(0)
	v_add_f32_e32 v15, v15, v20
	s_nop 1
	v_mov_b32_dpp v20, v15 row_half_mirror row_mask:0xf bank_mask:0xf
	s_waitcnt lgkmcnt(0)
	v_add_f32_e32 v15, v15, v20
	s_nop 1
	v_mov_b32_dpp v20, v15 row_mirror row_mask:0xf bank_mask:0xf
	s_waitcnt lgkmcnt(0)
	v_add_f32_e32 v15, v15, v20
	ds_bpermute_b32 v20, v32, v15
	s_waitcnt lgkmcnt(0)
	v_add_f32_e32 v15, v15, v20
	ds_bpermute_b32 v20, v33, v15
	s_waitcnt lgkmcnt(0)
	v_add_f32_e32 v15, v15, v20
	v_fmamk_f32 v15, v15, 0x3b800000, v187
	v_cmp_gt_f32_e32 vcc, s28, v15
	v_mul_f32_e32 v20, 0x4b800000, v15
	s_nop 0
	v_cndmask_b32_e32 v15, v15, v20, vcc
	v_rsq_f32_e32 v15, v15
	s_nop 0
	v_mul_f32_e32 v20, 0x45800000, v15
	v_cndmask_b32_e32 v20, v15, v20, vcc
	v_pk_mul_f32 v[0:1], v[0:1], v[20:21] op_sel_hi:[1,0]
	v_pk_mul_f32 v[2:3], v[2:3], v[20:21] op_sel_hi:[1,0]
	v_cvt_pk_bf16_f32 v0, v0, v1
	v_cvt_pk_bf16_f32 v1, v2, v3
	v_lshl_add_u64 v[2:3], v[18:19], 0, v[168:169]
	global_store_dwordx2 v[2:3], v[0:1], off offset:1536
	v_add_u32_e32 v0, 3, v14
	v_ashrrev_i32_e32 v1, 31, v0
	v_lshlrev_b64 v[14:15], 10, v[0:1]
	v_lshl_add_u64 v[12:13], v[12:13], 0, v[14:15]
	v_mov_b32_e32 v12, v216
	v_mov_b32_e32 v13, v217
	v_mov_b32_e32 v14, v218
	v_mov_b32_e32 v15, v219
	v_lshlrev_b64 v[2:3], 11, v[0:1]
	v_and_b32_e32 v19, 0xffff0000, v12
	v_lshlrev_b32_e32 v18, 16, v12
	v_mul_f32_e32 v24, v19, v19
	v_lshlrev_b32_e32 v22, 16, v13
	v_fmac_f32_e32 v24, v18, v18
	v_and_b32_e32 v23, 0xffff0000, v13
	v_fmac_f32_e32 v24, v22, v22
	v_and_b32_e32 v20, 0xffff0000, v14
	v_lshlrev_b32_e32 v21, 16, v14
	v_fmac_f32_e32 v24, v23, v23
	v_pk_mul_f32 v[12:13], v[20:21], v[20:21]
	v_and_b32_e32 v14, 0xffff0000, v15
	v_add_f32_e32 v13, v13, v24
	v_lshlrev_b32_e32 v15, 16, v15
	v_add_f32_e32 v24, v12, v13
	v_pk_mul_f32 v[12:13], v[14:15], v[14:15]
	s_nop 0
	v_add_f32_e32 v13, v13, v24
	v_add_f32_e32 v12, v12, v13
	s_nop 1
	v_mov_b32_dpp v13, v12 quad_perm:[1,0,3,2] row_mask:0xf bank_mask:0xf
	s_waitcnt lgkmcnt(0)
	v_add_f32_e32 v12, v12, v13
	s_nop 1
	v_mov_b32_dpp v13, v12 quad_perm:[2,3,0,1] row_mask:0xf bank_mask:0xf
	s_waitcnt lgkmcnt(0)
	v_add_f32_e32 v12, v12, v13
	s_nop 1
	v_mov_b32_dpp v13, v12 row_half_mirror row_mask:0xf bank_mask:0xf
	s_waitcnt lgkmcnt(0)
	v_add_f32_e32 v12, v12, v13
	s_nop 1
	v_mov_b32_dpp v13, v12 row_mirror row_mask:0xf bank_mask:0xf
	s_waitcnt lgkmcnt(0)
	v_add_f32_e32 v12, v12, v13
	ds_bpermute_b32 v13, v32, v12
	s_waitcnt lgkmcnt(0)
	v_add_f32_e32 v12, v12, v13
	ds_bpermute_b32 v13, v33, v12
	s_waitcnt lgkmcnt(0)
	v_add_f32_e32 v24, v12, v13
	v_lshl_add_u64 v[12:13], s[4:5], 0, v[2:3]
	v_fmamk_f32 v2, v24, 0x3b000000, v187
	v_cmp_gt_f32_e32 vcc, s28, v2
	v_mul_f32_e32 v3, 0x4b800000, v2
	s_nop 0
	v_cndmask_b32_e32 v2, v2, v3, vcc
	v_rsq_f32_e32 v2, v2
	s_nop 0
	v_mul_f32_e32 v3, 0x45800000, v2
	v_cndmask_b32_e32 v2, v2, v3, vcc
	v_mul_f32_e32 v3, v2, v18
	v_mul_f32_e32 v18, v2, v19
	v_cvt_pk_bf16_f32 v18, v3, v18
	v_mul_f32_e32 v3, v2, v22
	v_mul_f32_e32 v19, v2, v23
	v_cvt_pk_bf16_f32 v19, v3, v19
	v_mul_f32_e32 v3, v2, v21
	v_mul_f32_e32 v20, v2, v20
	v_cvt_pk_bf16_f32 v20, v3, v20
	v_mul_f32_e32 v3, v2, v15
	v_mul_f32_e32 v2, v2, v14
	v_cvt_pk_bf16_f32 v21, v3, v2
	v_lshl_add_u64 v[2:3], v[12:13], 0, v[6:7]
	global_store_dwordx4 v[2:3], v[18:21], off
	v_lshlrev_b64 v[2:3], 9, v[0:1]
	v_mad_i64_i32 v[0:1], s[0:1], v0, s93, v[16:17]
	v_lshl_add_u64 v[0:1], v[0:1], 0, v[168:169]
	v_lshl_add_u64 v[6:7], v[10:11], 0, v[2:3]
	v_lshl_add_u64 v[2:3], v[8:9], 0, v[2:3]
	v_add_co_u32_e32 v0, vcc, s29, v0
	v_mov_b32_e32 v10, v226
	v_mov_b32_e32 v11, v227
	s_nop 0
	v_addc_co_u32_e32 v1, vcc, 0, v1, vcc
	v_mov_b32_e32 v6, v234
	v_mov_b32_e32 v7, v235
	v_mov_b32_e32 v14, v242
	v_mov_b32_e32 v15, v243
	s_nop 0
	v_mov_b32_e32 v0, v248
	v_mov_b32_e32 v1, v249
	v_mov_b32_e32 v2, v250
	v_mov_b32_e32 v3, v251
	v_lshlrev_b32_e32 v4, 16, v11
	v_and_b32_e32 v5, 0xffff0000, v11
	v_lshlrev_b32_e32 v8, 16, v7
	v_and_b32_e32 v9, 0xffff0000, v7
	v_lshlrev_b32_e32 v16, 16, v15
	v_and_b32_e32 v17, 0xffff0000, v15
	v_mul_f32_e32 v7, 0x3d372713, v16
	v_pk_fma_f32 v[2:3], v[2:3], v[8:9], v[4:5]
	v_mul_f32_e32 v4, 0x3d372713, v17
	v_mul_f32_e32 v7, v7, v16
	v_mov_b32_e32 v11, v16
	v_mul_f32_e32 v4, v4, v17
	v_mov_b32_e32 v5, v17
	v_fmac_f32_e32 v11, v7, v11
	v_fmac_f32_e32 v5, v4, v5
	v_mul_f32_e32 v7, 0x3f4c422a, v11
	v_mul_f32_e32 v4, 0x3f4c422a, v5
	v_add_f32_e32 v7, v7, v7
	v_add_f32_e32 v4, v4, v4
	v_mul_f32_e32 v7, 0x3fb8aa3b, v7
	v_mul_f32_e32 v4, 0x3fb8aa3b, v4
	v_exp_f32_e32 v18, v7
	v_exp_f32_e32 v19, v4
	s_nop 0
	v_pk_add_f32 v[4:5], v[18:19], 1.0 op_sel_hi:[1,0]
	s_nop 0
	v_div_scale_f32 v7, s[0:1], v5, v5, 2.0
	v_rcp_f32_e32 v8, v7
	s_nop 0
	v_fma_f32 v9, -v7, v8, 1.0
	v_fmac_f32_e32 v8, v9, v8
	v_div_scale_f32 v9, vcc, 2.0, v5, 2.0
	v_mul_f32_e32 v11, v9, v8
	v_fma_f32 v15, -v7, v11, v9
	v_fmac_f32_e32 v11, v15, v8
	v_fma_f32 v7, -v7, v11, v9
	v_div_fmas_f32 v7, v7, v8, v11
	v_div_fixup_f32 v5, v7, v5, 2.0
	v_div_scale_f32 v7, s[0:1], v4, v4, 2.0
	v_rcp_f32_e32 v8, v7
	s_nop 0
	v_fma_f32 v9, -v7, v8, 1.0
	v_fmac_f32_e32 v8, v9, v8
	v_div_scale_f32 v9, vcc, 2.0, v4, 2.0
	v_mul_f32_e32 v11, v9, v8
	v_fma_f32 v15, -v7, v11, v9
	v_fmac_f32_e32 v11, v15, v8
	v_fma_f32 v7, -v7, v11, v9
	v_div_fmas_f32 v7, v7, v8, v11
	v_div_fixup_f32 v4, v7, v4, 2.0
	v_pk_add_f32 v[4:5], v[4:5], 1.0 op_sel_hi:[1,0] neg_lo:[1,0] neg_hi:[1,0]
	v_pk_mul_f32 v[8:9], v[16:17], 0.5 op_sel_hi:[1,0]
	v_pk_add_f32 v[4:5], v[4:5], 1.0 op_sel_hi:[1,0]
	v_lshlrev_b32_e32 v16, 16, v10
	v_pk_mul_f32 v[4:5], v[8:9], v[4:5]
	v_lshlrev_b32_e32 v8, 16, v14
	v_and_b32_e32 v17, 0xffff0000, v10
	v_lshlrev_b32_e32 v10, 16, v6
	v_and_b32_e32 v11, 0xffff0000, v6
	v_mul_f32_e32 v6, 0x3d372713, v8
	v_mul_f32_e32 v6, v6, v8
	v_mov_b32_e32 v7, v8
	v_and_b32_e32 v9, 0xffff0000, v14
	v_fmac_f32_e32 v7, v6, v7
	v_mul_f32_e32 v6, 0x3f4c422a, v7
	v_mul_f32_e32 v7, 0x3d372713, v9
	v_pk_fma_f32 v[0:1], v[0:1], v[10:11], v[16:17]
	v_mul_f32_e32 v7, v7, v9
	v_mov_b32_e32 v10, v9
	v_fmac_f32_e32 v10, v7, v10
	v_mul_f32_e32 v7, 0x3f4c422a, v10
	v_add_f32_e32 v6, v6, v6
	v_add_f32_e32 v7, v7, v7
	v_mul_f32_e32 v6, 0x3fb8aa3b, v6
	v_mul_f32_e32 v7, 0x3fb8aa3b, v7
	v_exp_f32_e32 v6, v6
	v_exp_f32_e32 v7, v7
	v_pk_mul_f32 v[8:9], v[8:9], 0.5 op_sel_hi:[1,0]
	v_pk_mul_f32 v[2:3], v[2:3], v[4:5]
	v_pk_add_f32 v[6:7], v[6:7], 1.0 op_sel_hi:[1,0]
	s_nop 0
	v_div_scale_f32 v10, s[0:1], v7, v7, 2.0
	v_rcp_f32_e32 v11, v10
	v_pk_mul_f32 v[4:5], v[2:3], v[2:3]
	v_fma_f32 v14, -v10, v11, 1.0
	v_fmac_f32_e32 v11, v14, v11
	v_div_scale_f32 v14, vcc, 2.0, v7, 2.0
	v_mul_f32_e32 v15, v14, v11
	v_fma_f32 v16, -v10, v15, v14
	v_fmac_f32_e32 v15, v16, v11
	v_fma_f32 v10, -v10, v15, v14
	v_div_fmas_f32 v10, v10, v11, v15
	v_div_fixup_f32 v7, v10, v7, 2.0
	v_div_scale_f32 v10, s[0:1], v6, v6, 2.0
	v_rcp_f32_e32 v11, v10
	s_nop 0
	v_fma_f32 v14, -v10, v11, 1.0
	v_fmac_f32_e32 v11, v14, v11
	v_div_scale_f32 v14, vcc, 2.0, v6, 2.0
	v_mul_f32_e32 v15, v14, v11
	v_fma_f32 v16, -v10, v15, v14
	v_fmac_f32_e32 v15, v16, v11
	v_fma_f32 v10, -v10, v15, v14
	v_div_fmas_f32 v10, v10, v11, v15
	v_div_fixup_f32 v6, v10, v6, 2.0
	v_pk_add_f32 v[6:7], v[6:7], 1.0 op_sel_hi:[1,0] neg_lo:[1,0] neg_hi:[1,0]
	s_nop 0
	v_pk_add_f32 v[6:7], v[6:7], 1.0 op_sel_hi:[1,0]
	s_nop 0
	v_pk_mul_f32 v[6:7], v[8:9], v[6:7]
	s_nop 0
	v_pk_mul_f32 v[0:1], v[0:1], v[6:7]
	s_nop 0
	v_pk_mul_f32 v[6:7], v[0:1], v[0:1]
	s_nop 0
	v_add_f32_e32 v6, v6, v7
	v_add_f32_e32 v4, v4, v6
	v_add_f32_e32 v4, v5, v4
	s_nop 1
	v_mov_b32_dpp v5, v4 quad_perm:[1,0,3,2] row_mask:0xf bank_mask:0xf
	s_waitcnt lgkmcnt(0)
	v_add_f32_e32 v4, v4, v5
	s_nop 1
	v_mov_b32_dpp v5, v4 quad_perm:[2,3,0,1] row_mask:0xf bank_mask:0xf
	s_waitcnt lgkmcnt(0)
	v_add_f32_e32 v4, v4, v5
	s_nop 1
	v_mov_b32_dpp v5, v4 row_half_mirror row_mask:0xf bank_mask:0xf
	s_waitcnt lgkmcnt(0)
	v_add_f32_e32 v4, v4, v5
	s_nop 1
	v_mov_b32_dpp v5, v4 row_mirror row_mask:0xf bank_mask:0xf
	s_waitcnt lgkmcnt(0)
	v_add_f32_e32 v4, v4, v5
	ds_bpermute_b32 v5, v32, v4
	s_waitcnt lgkmcnt(0)
	v_add_f32_e32 v4, v4, v5
	ds_bpermute_b32 v5, v33, v4
	s_waitcnt lgkmcnt(0)
	v_add_f32_e32 v4, v4, v5
	v_fmamk_f32 v4, v4, 0x3b800000, v187
	v_cmp_gt_f32_e32 vcc, s28, v4
	v_mul_f32_e32 v5, 0x4b800000, v4
	s_nop 0
	v_cndmask_b32_e32 v4, v4, v5, vcc
	v_rsq_f32_e32 v4, v4
	s_nop 0
	v_mul_f32_e32 v5, 0x45800000, v4
	v_cndmask_b32_e32 v4, v4, v5, vcc
	v_pk_mul_f32 v[0:1], v[0:1], v[4:5] op_sel_hi:[1,0]
	v_pk_mul_f32 v[2:3], v[2:3], v[4:5] op_sel_hi:[1,0]
	v_cvt_pk_bf16_f32 v0, v0, v1
	v_cvt_pk_bf16_f32 v1, v2, v3
	v_lshl_add_u64 v[2:3], v[12:13], 0, v[168:169]
	global_store_dwordx2 v[2:3], v[0:1], off offset:1536
	s_cbranch_execnz .LBB0_803
